# grid barrier: generation at each barrier site is its static index (barrier words zeroed per launch), removing the two runtime integer divisions from the arrival critical path
# baseline (speedup 1.0000x reference)
.LBB0_60:
	s_or_b64 exec, exec, s[8:9]
	s_waitcnt vmcnt(0)
	buffer_inv sc1
	v_readfirstlane_b32 s3, v3
	v_add_u32_e32 v5, s3, v1
	v_add_u32_e32 v3, 1, v5
	v_mov_b32_e32 v1, 0
	v_mul_u32_u24_e32 v4, 0, v2
	v_add_u32_e32 v2, v4, v2
	v_cmp_ne_u32_e32 vcc, v3, v2
	s_and_saveexec_b64 s[6:7], vcc
	s_xor_b64 s[6:7], exec, s[6:7]
	s_cbranch_execz .LBB0_74
	s_waitcnt lgkmcnt(0)
	v_add_u32_e32 v1, 1, v1
	v_mul_lo_u32 v1, v1, v0
	s_add_u32 s12, s24, 0xed25400
	s_addc_u32 s13, s25, 0
	v_mov_b32_e32 v0, 0
	global_load_dword v0, v0, s[12:13] sc1
	s_waitcnt vmcnt(0)
	v_cmp_lt_u32_e32 vcc, v0, v1
	s_and_saveexec_b64 s[8:9], vcc
	s_cbranch_execz .LBB0_73
	s_add_u32 s10, s24, 0xed22200
	s_addc_u32 s11, s25, 0
	s_mov_b32 s3, 1
	s_mov_b64 s[14:15], 0
	v_mov_b32_e32 v0, 0
	s_branch .LBB0_64

.LBB0_77:
	s_or_b64 exec, exec, s[8:9]
	s_waitcnt vmcnt(0)
	v_readfirstlane_b32 s3, v2
	s_add_u32 s8, s24, 0xed25400
	s_addc_u32 s9, s25, 0
	s_mov_b64 s[10:11], 0
	v_add_u32_e32 v1, s3, v1
	v_add_u32_e32 v4, 1, v1
	v_mul_u32_u24_e32 v0, 1, v0
	v_cmp_ne_u32_e32 vcc, v4, v0
	v_readfirstlane_b32 s100, v0
	v_mov_b64_e32 v[0:1], s[8:9]
	s_and_saveexec_b64 s[6:7], vcc
	s_cbranch_execz .LBB0_89
	v_mov_b32_e32 v0, 0
	global_load_dword v1, v0, s[8:9] sc1
	s_mov_b64 s[14:15], 0
	s_waitcnt vmcnt(0)
	v_cmp_gt_u32_e32 vcc, s100, v1
	s_and_saveexec_b64 s[12:13], vcc
	s_cbranch_execz .LBB0_88
	s_add_u32 s10, s24, 0xed22200
	s_addc_u32 s11, s25, 0
	s_mov_b32 s3, 1
	s_branch .LBB0_81

.LBB0_188:
	s_or_b64 exec, exec, s[8:9]
	s_waitcnt vmcnt(0)
	buffer_inv sc1
	v_readfirstlane_b32 s3, v3
	v_add_u32_e32 v5, s3, v1
	v_add_u32_e32 v3, 1, v5
	v_mov_b32_e32 v1, 1
	v_mul_u32_u24_e32 v4, 1, v2
	v_add_u32_e32 v2, v4, v2
	v_cmp_ne_u32_e32 vcc, v3, v2
	s_and_saveexec_b64 s[6:7], vcc
	s_xor_b64 s[6:7], exec, s[6:7]
	s_cbranch_execz .LBB0_202
	s_waitcnt lgkmcnt(0)
	v_add_u32_e32 v1, 1, v1
	v_mul_lo_u32 v1, v1, v0
	s_add_u32 s12, s24, 0xed25400
	s_addc_u32 s13, s25, 0
	v_mov_b32_e32 v0, 0
	global_load_dword v0, v0, s[12:13] sc1
	s_waitcnt vmcnt(0)
	v_cmp_lt_u32_e32 vcc, v0, v1
	s_and_saveexec_b64 s[8:9], vcc
	s_cbranch_execz .LBB0_201
	s_add_u32 s10, s24, 0xed22200
	s_addc_u32 s11, s25, 0
	s_mov_b32 s3, 1
	s_mov_b64 s[14:15], 0
	v_mov_b32_e32 v0, 0
	s_branch .LBB0_192

.LBB0_205:
	s_or_b64 exec, exec, s[10:11]
	s_waitcnt vmcnt(0)
	v_readfirstlane_b32 s3, v2
	s_add_u32 s10, s24, 0xed25400
	s_addc_u32 s11, s25, 0
	s_mov_b64 s[12:13], 0
	v_add_u32_e32 v1, s3, v1
	v_add_u32_e32 v4, 1, v1
	v_mul_u32_u24_e32 v0, 2, v0
	v_cmp_ne_u32_e32 vcc, v4, v0
	v_readfirstlane_b32 s100, v0
	v_mov_b64_e32 v[0:1], s[10:11]
	s_and_saveexec_b64 s[8:9], vcc
	s_cbranch_execz .LBB0_217
	v_mov_b32_e32 v0, 0
	global_load_dword v1, v0, s[10:11] sc1
	s_mov_b64 s[16:17], 0
	s_waitcnt vmcnt(0)
	v_cmp_gt_u32_e32 vcc, s100, v1
	s_and_saveexec_b64 s[14:15], vcc
	s_cbranch_execz .LBB0_216
	s_add_u32 s12, s24, 0xed22200
	s_addc_u32 s13, s25, 0
	s_mov_b32 s3, 1
	s_mov_b64 s[34:35], 0
	s_branch .LBB0_209

.LBB0_779:
	s_or_b64 exec, exec, s[8:9]
	s_waitcnt vmcnt(0)
	buffer_inv sc1
	v_readfirstlane_b32 s3, v3
	v_add_u32_e32 v5, s3, v1
	v_add_u32_e32 v3, 1, v5
	v_mov_b32_e32 v1, 2
	v_mul_u32_u24_e32 v4, 2, v2
	v_add_u32_e32 v2, v4, v2
	v_cmp_ne_u32_e32 vcc, v3, v2
	s_and_saveexec_b64 s[6:7], vcc
	s_xor_b64 s[6:7], exec, s[6:7]
	s_cbranch_execz .LBB0_793
	s_waitcnt lgkmcnt(0)
	v_add_u32_e32 v1, 1, v1
	v_mul_lo_u32 v1, v1, v0
	s_add_u32 s12, s24, 0xed25400
	s_addc_u32 s13, s25, 0
	v_mov_b32_e32 v0, 0
	global_load_dword v0, v0, s[12:13] sc1
	s_waitcnt vmcnt(0)
	v_cmp_lt_u32_e32 vcc, v0, v1
	s_and_saveexec_b64 s[8:9], vcc
	s_cbranch_execz .LBB0_792
	s_add_u32 s10, s24, 0xed22200
	s_addc_u32 s11, s25, 0
	s_mov_b32 s3, 1
	s_mov_b64 s[14:15], 0
	v_mov_b32_e32 v0, 0
	s_branch .LBB0_783

.LBB0_796:
	s_or_b64 exec, exec, s[10:11]
	s_waitcnt vmcnt(0)
	v_readfirstlane_b32 s3, v2
	s_add_u32 s10, s24, 0xed25400
	s_addc_u32 s11, s25, 0
	s_mov_b64 s[12:13], 0
	v_add_u32_e32 v1, s3, v1
	v_add_u32_e32 v4, 1, v1
	v_mul_u32_u24_e32 v0, 3, v0
	v_cmp_ne_u32_e32 vcc, v4, v0
	v_readfirstlane_b32 s100, v0
	v_mov_b64_e32 v[0:1], s[10:11]
	s_and_saveexec_b64 s[8:9], vcc
	s_cbranch_execz .LBB0_808
	v_mov_b32_e32 v0, 0
	global_load_dword v1, v0, s[10:11] sc1
	s_mov_b64 s[16:17], 0
	s_waitcnt vmcnt(0)
	v_cmp_gt_u32_e32 vcc, s100, v1
	s_and_saveexec_b64 s[14:15], vcc
	s_cbranch_execz .LBB0_807
	s_add_u32 s12, s24, 0xed22200
	s_addc_u32 s13, s25, 0
	s_mov_b32 s3, 1
	s_mov_b64 s[56:57], 0
	s_branch .LBB0_800

.LBB0_954:
	s_or_b64 exec, exec, s[12:13]
	s_waitcnt vmcnt(0)
	buffer_inv sc1
	v_readfirstlane_b32 s3, v3
	v_add_u32_e32 v5, s3, v1
	v_add_u32_e32 v3, 1, v5
	v_mov_b32_e32 v1, 3
	v_mul_u32_u24_e32 v4, 3, v2
	v_add_u32_e32 v2, v4, v2
	v_cmp_ne_u32_e32 vcc, v3, v2
	s_and_saveexec_b64 s[10:11], vcc
	s_xor_b64 s[10:11], exec, s[10:11]
	s_cbranch_execz .LBB0_968
	s_waitcnt lgkmcnt(0)
	v_add_u32_e32 v1, 1, v1
	v_mul_lo_u32 v1, v1, v0
	s_add_u32 s42, s24, 0xed25400
	s_addc_u32 s43, s25, 0
	v_mov_b32_e32 v0, 0
	global_load_dword v0, v0, s[42:43] sc1
	s_waitcnt vmcnt(0)
	v_cmp_lt_u32_e32 vcc, v0, v1
	s_and_saveexec_b64 s[12:13], vcc
	s_cbranch_execz .LBB0_967
	s_add_u32 s40, s24, 0xed22200
	s_addc_u32 s41, s25, 0
	s_mov_b32 s3, 1
	s_mov_b64 s[46:47], 0
	v_mov_b32_e32 v0, 0
	s_branch .LBB0_958

.LBB0_971:
	s_or_b64 exec, exec, s[16:17]
	s_waitcnt vmcnt(0)
	v_readfirstlane_b32 s3, v2
	s_add_u32 s40, s24, 0xed25400
	s_addc_u32 s41, s25, 0
	s_mov_b64 s[16:17], 0
	v_add_u32_e32 v1, s3, v1
	v_add_u32_e32 v4, 1, v1
	v_mul_u32_u24_e32 v0, 4, v0
	v_cmp_ne_u32_e32 vcc, v4, v0
	v_readfirstlane_b32 s100, v0
	v_mov_b64_e32 v[0:1], s[40:41]
	s_and_saveexec_b64 s[12:13], vcc
	s_cbranch_execz .LBB0_983
	v_mov_b32_e32 v0, 0
	global_load_dword v1, v0, s[40:41] sc1
	s_mov_b64 s[16:17], 0
	s_waitcnt vmcnt(0)
	v_cmp_gt_u32_e32 vcc, s100, v1
	s_and_saveexec_b64 s[46:47], vcc
	s_cbranch_execz .LBB0_982
	s_add_u32 s42, s24, 0xed22200
	s_addc_u32 s43, s25, 0
	s_mov_b32 s3, 1
	s_mov_b64 s[48:49], 0
	s_branch .LBB0_975

.LBB0_1024:
	s_or_b64 exec, exec, s[12:13]
	s_waitcnt vmcnt(0)
	buffer_inv sc1
	v_readfirstlane_b32 s3, v3
	v_add_u32_e32 v5, s3, v1
	v_add_u32_e32 v3, 1, v5
	v_mov_b32_e32 v1, 4
	v_mul_u32_u24_e32 v4, 4, v2
	v_add_u32_e32 v2, v4, v2
	v_cmp_ne_u32_e32 vcc, v3, v2
	s_and_saveexec_b64 s[10:11], vcc
	s_xor_b64 s[10:11], exec, s[10:11]
	s_cbranch_execz .LBB0_1038
	s_waitcnt lgkmcnt(0)
	v_add_u32_e32 v1, 1, v1
	v_mul_lo_u32 v1, v1, v0
	s_add_u32 s42, s24, 0xed25400
	s_addc_u32 s43, s25, 0
	v_mov_b32_e32 v0, 0
	global_load_dword v0, v0, s[42:43] sc1
	s_waitcnt vmcnt(0)
	v_cmp_lt_u32_e32 vcc, v0, v1
	s_and_saveexec_b64 s[12:13], vcc
	s_cbranch_execz .LBB0_1037
	s_add_u32 s40, s24, 0xed22200
	s_addc_u32 s41, s25, 0
	s_mov_b32 s3, 1
	s_mov_b64 s[46:47], 0
	v_mov_b32_e32 v0, 0
	s_branch .LBB0_1028

.LBB0_1041:
	s_or_b64 exec, exec, s[16:17]
	s_waitcnt vmcnt(0)
	v_readfirstlane_b32 s3, v2
	s_add_u32 s40, s24, 0xed25400
	s_addc_u32 s41, s25, 0
	s_mov_b64 s[16:17], 0
	v_add_u32_e32 v1, s3, v1
	v_add_u32_e32 v4, 1, v1
	v_mul_u32_u24_e32 v0, 5, v0
	v_cmp_ne_u32_e32 vcc, v4, v0
	v_readfirstlane_b32 s100, v0
	v_mov_b64_e32 v[0:1], s[40:41]
	s_and_saveexec_b64 s[12:13], vcc
	s_cbranch_execz .LBB0_1053
	v_mov_b32_e32 v0, 0
	global_load_dword v1, v0, s[40:41] sc1
	s_mov_b64 s[16:17], 0
	s_waitcnt vmcnt(0)
	v_cmp_gt_u32_e32 vcc, s100, v1
	s_and_saveexec_b64 s[46:47], vcc
	s_cbranch_execz .LBB0_1052
	s_add_u32 s42, s24, 0xed22200
	s_addc_u32 s43, s25, 0
	s_mov_b32 s3, 1
	s_mov_b64 s[48:49], 0
	s_branch .LBB0_1045

.LBB0_1090:
	s_or_b64 exec, exec, s[16:17]
	s_waitcnt vmcnt(0)
	buffer_inv sc1
	v_readfirstlane_b32 s3, v3
	v_add_u32_e32 v5, s3, v1
	v_add_u32_e32 v3, 1, v5
	v_mov_b32_e32 v1, 5
	v_mul_u32_u24_e32 v4, 5, v2
	v_add_u32_e32 v2, v4, v2
	v_cmp_ne_u32_e32 vcc, v3, v2
	s_and_saveexec_b64 s[6:7], vcc
	s_xor_b64 s[6:7], exec, s[6:7]
	s_cbranch_execz .LBB0_1104
	s_waitcnt lgkmcnt(0)
	v_add_u32_e32 v1, 1, v1
	v_mul_lo_u32 v1, v1, v0
	s_add_u32 s46, s24, 0xed25400
	s_addc_u32 s47, s25, 0
	v_mov_b32_e32 v0, 0
	global_load_dword v0, v0, s[46:47] sc1
	s_waitcnt vmcnt(0)
	v_cmp_lt_u32_e32 vcc, v0, v1
	s_and_saveexec_b64 s[40:41], vcc
	s_cbranch_execz .LBB0_1103
	s_add_u32 s42, s24, 0xed22200
	s_addc_u32 s43, s25, 0
	s_mov_b32 s3, 1
	s_mov_b64 s[48:49], 0
	v_mov_b32_e32 v0, 0
	s_branch .LBB0_1094

.LBB0_1107:
	s_or_b64 exec, exec, s[28:29]
	s_waitcnt vmcnt(0)
	v_readfirstlane_b32 s3, v2
	s_add_u32 s42, s24, 0xed25400
	s_addc_u32 s43, s25, 0
	s_mov_b64 s[16:17], 0
	v_add_u32_e32 v1, s3, v1
	v_add_u32_e32 v4, 1, v1
	v_mul_u32_u24_e32 v0, 6, v0
	v_cmp_ne_u32_e32 vcc, v4, v0
	v_readfirstlane_b32 s100, v0
	v_mov_b64_e32 v[0:1], s[42:43]
	s_and_saveexec_b64 s[40:41], vcc
	s_cbranch_execz .LBB0_1119
	v_mov_b32_e32 v0, 0
	global_load_dword v1, v0, s[42:43] sc1
	s_mov_b64 s[16:17], 0
	s_waitcnt vmcnt(0)
	v_cmp_gt_u32_e32 vcc, s100, v1
	s_and_saveexec_b64 s[48:49], vcc
	s_cbranch_execz .LBB0_1118
	s_add_u32 s46, s24, 0xed22200
	s_addc_u32 s47, s25, 0
	s_mov_b32 s3, 1
	s_mov_b64 s[52:53], 0
	s_branch .LBB0_1111

.LBB0_1220:
	s_or_b64 exec, exec, s[16:17]
	s_waitcnt vmcnt(0)
	buffer_inv sc1
	v_readfirstlane_b32 s3, v3
	v_add_u32_e32 v5, s3, v1
	v_add_u32_e32 v3, 1, v5
	v_mov_b32_e32 v1, 6
	v_mul_u32_u24_e32 v4, 6, v2
	v_add_u32_e32 v2, v4, v2
	v_cmp_ne_u32_e32 vcc, v3, v2
	s_and_saveexec_b64 s[6:7], vcc
	s_xor_b64 s[6:7], exec, s[6:7]
	s_cbranch_execz .LBB0_1234
	s_waitcnt lgkmcnt(0)
	v_add_u32_e32 v1, 1, v1
	v_mul_lo_u32 v1, v1, v0
	s_add_u32 s40, s24, 0xed25400
	s_addc_u32 s41, s25, 0
	v_mov_b32_e32 v0, 0
	global_load_dword v0, v0, s[40:41] sc1
	s_waitcnt vmcnt(0)
	v_cmp_lt_u32_e32 vcc, v0, v1
	s_and_saveexec_b64 s[36:37], vcc
	s_cbranch_execz .LBB0_1233
	s_add_u32 s38, s24, 0xed22200
	s_addc_u32 s39, s25, 0
	s_mov_b32 s3, 1
	s_mov_b64 s[42:43], 0
	v_mov_b32_e32 v0, 0
	s_branch .LBB0_1224

.LBB0_1237:
	s_or_b64 exec, exec, s[16:17]
	s_waitcnt vmcnt(0)
	v_readfirstlane_b32 s3, v2
	s_add_u32 s36, s24, 0xed25400
	s_addc_u32 s37, s25, 0
	s_mov_b64 s[16:17], 0
	v_add_u32_e32 v1, s3, v1
	v_add_u32_e32 v4, 1, v1
	v_mul_u32_u24_e32 v0, 7, v0
	v_cmp_ne_u32_e32 vcc, v4, v0
	v_readfirstlane_b32 s100, v0
	v_mov_b64_e32 v[0:1], s[36:37]
	s_and_saveexec_b64 s[6:7], vcc
	s_cbranch_execz .LBB0_1249
	v_mov_b32_e32 v0, 0
	global_load_dword v1, v0, s[36:37] sc1
	s_mov_b64 s[16:17], 0
	s_waitcnt vmcnt(0)
	v_cmp_gt_u32_e32 vcc, s100, v1
	s_and_saveexec_b64 s[40:41], vcc
	s_cbranch_execz .LBB0_1248
	s_add_u32 s38, s24, 0xed22200
	s_addc_u32 s39, s25, 0
	s_mov_b32 s3, 1
	s_mov_b64 s[42:43], 0
	s_branch .LBB0_1241

.LBB0_1318:
	s_or_b64 exec, exec, s[14:15]
	s_waitcnt vmcnt(0)
	buffer_inv sc1
	v_readfirstlane_b32 s3, v3
	v_add_u32_e32 v5, s3, v1
	v_add_u32_e32 v3, 1, v5
	v_mov_b32_e32 v1, 7
	v_mul_u32_u24_e32 v4, 7, v2
	v_add_u32_e32 v2, v4, v2
	v_cmp_ne_u32_e32 vcc, v3, v2
	s_and_saveexec_b64 s[6:7], vcc
	s_xor_b64 s[6:7], exec, s[6:7]
	s_cbranch_execz .LBB0_1332
	s_waitcnt lgkmcnt(0)
	v_add_u32_e32 v1, 1, v1
	v_mul_lo_u32 v1, v1, v0
	s_add_u32 s38, s24, 0xed25400
	s_addc_u32 s39, s25, 0
	v_mov_b32_e32 v0, 0
	global_load_dword v0, v0, s[38:39] sc1
	s_waitcnt vmcnt(0)
	v_cmp_lt_u32_e32 vcc, v0, v1
	s_and_saveexec_b64 s[14:15], vcc
	s_cbranch_execz .LBB0_1331
	s_add_u32 s36, s24, 0xed22200
	s_addc_u32 s37, s25, 0
	s_mov_b32 s3, 1
	s_mov_b64 s[40:41], 0
	v_mov_b32_e32 v0, 0
	s_branch .LBB0_1322

.LBB0_1335:
	s_or_b64 exec, exec, s[16:17]
	s_waitcnt vmcnt(0)
	v_readfirstlane_b32 s3, v2
	s_add_u32 s36, s24, 0xed25400
	s_addc_u32 s37, s25, 0
	s_mov_b64 s[16:17], 0
	v_add_u32_e32 v1, s3, v1
	v_add_u32_e32 v4, 1, v1
	v_mul_u32_u24_e32 v0, 8, v0
	v_cmp_ne_u32_e32 vcc, v4, v0
	v_readfirstlane_b32 s100, v0
	v_mov_b64_e32 v[0:1], s[36:37]
	s_and_saveexec_b64 s[14:15], vcc
	s_cbranch_execz .LBB0_1347
	v_mov_b32_e32 v0, 0
	global_load_dword v1, v0, s[36:37] sc1
	s_mov_b64 s[16:17], 0
	s_waitcnt vmcnt(0)
	v_cmp_gt_u32_e32 vcc, s100, v1
	s_and_saveexec_b64 s[40:41], vcc
	s_cbranch_execz .LBB0_1346
	s_add_u32 s38, s24, 0xed22200
	s_addc_u32 s39, s25, 0
	s_mov_b32 s3, 1
	s_mov_b64 s[42:43], 0
	s_branch .LBB0_1339

.LBB0_1391:
	s_or_b64 exec, exec, s[14:15]
	s_waitcnt vmcnt(0)
	buffer_inv sc1
	v_readfirstlane_b32 s3, v3
	v_add_u32_e32 v5, s3, v1
	v_add_u32_e32 v3, 1, v5
	v_mov_b32_e32 v1, 8
	v_mul_u32_u24_e32 v4, 8, v2
	v_add_u32_e32 v2, v4, v2
	v_cmp_ne_u32_e32 vcc, v3, v2
	s_and_saveexec_b64 s[6:7], vcc
	s_xor_b64 s[6:7], exec, s[6:7]
	s_cbranch_execz .LBB0_1405
	s_waitcnt lgkmcnt(0)
	v_add_u32_e32 v1, 1, v1
	v_mul_lo_u32 v1, v1, v0
	s_add_u32 s38, s24, 0xed25400
	s_addc_u32 s39, s25, 0
	v_mov_b32_e32 v0, 0
	global_load_dword v0, v0, s[38:39] sc1
	s_waitcnt vmcnt(0)
	v_cmp_lt_u32_e32 vcc, v0, v1
	s_and_saveexec_b64 s[14:15], vcc
	s_cbranch_execz .LBB0_1404
	s_add_u32 s36, s24, 0xed22200
	s_addc_u32 s37, s25, 0
	s_mov_b32 s3, 1
	s_mov_b64 s[40:41], 0
	v_mov_b32_e32 v0, 0
	s_branch .LBB0_1395

.LBB0_1408:
	s_or_b64 exec, exec, s[16:17]
	s_waitcnt vmcnt(0)
	v_readfirstlane_b32 s3, v2
	s_add_u32 s36, s24, 0xed25400
	s_addc_u32 s37, s25, 0
	s_mov_b64 s[16:17], 0
	v_add_u32_e32 v1, s3, v1
	v_add_u32_e32 v4, 1, v1
	v_mul_u32_u24_e32 v0, 9, v0
	v_cmp_ne_u32_e32 vcc, v4, v0
	v_readfirstlane_b32 s100, v0
	v_mov_b64_e32 v[0:1], s[36:37]
	s_and_saveexec_b64 s[14:15], vcc
	s_cbranch_execz .LBB0_1420
	v_mov_b32_e32 v0, 0
	global_load_dword v1, v0, s[36:37] sc1
	s_mov_b64 s[16:17], 0
	s_waitcnt vmcnt(0)
	v_cmp_gt_u32_e32 vcc, s100, v1
	s_and_saveexec_b64 s[40:41], vcc
	s_cbranch_execz .LBB0_1419
	s_add_u32 s38, s24, 0xed22200
	s_addc_u32 s39, s25, 0
	s_mov_b32 s3, 1
	s_mov_b64 s[42:43], 0
	s_branch .LBB0_1412

.LBB0_1457:
	s_or_b64 exec, exec, s[14:15]
	s_waitcnt vmcnt(0)
	buffer_inv sc1
	v_readfirstlane_b32 s3, v3
	v_add_u32_e32 v5, s3, v1
	v_add_u32_e32 v3, 1, v5
	v_mov_b32_e32 v1, 9
	v_mul_u32_u24_e32 v4, 9, v2
	v_add_u32_e32 v2, v4, v2
	v_cmp_ne_u32_e32 vcc, v3, v2
	s_and_saveexec_b64 s[6:7], vcc
	s_xor_b64 s[6:7], exec, s[6:7]
	s_cbranch_execz .LBB0_1471
	s_waitcnt lgkmcnt(0)
	v_add_u32_e32 v1, 1, v1
	v_mul_lo_u32 v1, v1, v0
	s_add_u32 s38, s24, 0xed25400
	s_addc_u32 s39, s25, 0
	v_mov_b32_e32 v0, 0
	global_load_dword v0, v0, s[38:39] sc1
	s_waitcnt vmcnt(0)
	v_cmp_lt_u32_e32 vcc, v0, v1
	s_and_saveexec_b64 s[14:15], vcc
	s_cbranch_execz .LBB0_1470
	s_add_u32 s36, s24, 0xed22200
	s_addc_u32 s37, s25, 0
	s_mov_b32 s3, 1
	s_mov_b64 s[40:41], 0
	v_mov_b32_e32 v0, 0
	s_branch .LBB0_1461

.LBB0_1474:
	s_or_b64 exec, exec, s[16:17]
	s_waitcnt vmcnt(0)
	v_readfirstlane_b32 s3, v2
	s_add_u32 s36, s24, 0xed25400
	s_addc_u32 s37, s25, 0
	s_mov_b64 s[16:17], 0
	v_add_u32_e32 v1, s3, v1
	v_add_u32_e32 v4, 1, v1
	v_mul_u32_u24_e32 v0, 10, v0
	v_cmp_ne_u32_e32 vcc, v4, v0
	v_readfirstlane_b32 s100, v0
	v_mov_b64_e32 v[0:1], s[36:37]
	s_and_saveexec_b64 s[14:15], vcc
	s_cbranch_execz .LBB0_1486
	v_mov_b32_e32 v0, 0
	global_load_dword v1, v0, s[36:37] sc1
	s_mov_b64 s[16:17], 0
	s_waitcnt vmcnt(0)
	v_cmp_gt_u32_e32 vcc, s100, v1
	s_and_saveexec_b64 s[40:41], vcc
	s_cbranch_execz .LBB0_1485
	s_add_u32 s38, s24, 0xed22200
	s_addc_u32 s39, s25, 0
	s_mov_b32 s3, 1
	s_mov_b64 s[42:43], 0
	s_branch .LBB0_1478

.LBB0_1522:
	s_or_b64 exec, exec, s[8:9]
	s_waitcnt vmcnt(0)
	buffer_inv sc1
	v_readfirstlane_b32 s6, v3
	v_add_u32_e32 v5, s6, v1
	v_add_u32_e32 v3, 1, v5
	v_mov_b32_e32 v1, 10
	v_mul_u32_u24_e32 v4, 10, v2
	v_add_u32_e32 v2, v4, v2
	v_cmp_ne_u32_e32 vcc, v3, v2
	s_and_saveexec_b64 s[6:7], vcc
	s_xor_b64 s[6:7], exec, s[6:7]
	s_cbranch_execz .LBB0_1536
	s_waitcnt lgkmcnt(0)
	v_add_u32_e32 v1, 1, v1
	v_mul_lo_u32 v1, v1, v0
	s_add_u32 s14, s24, 0xed25400
	s_addc_u32 s15, s25, 0
	v_mov_b32_e32 v0, 0
	global_load_dword v0, v0, s[14:15] sc1
	s_waitcnt vmcnt(0)
	v_cmp_lt_u32_e32 vcc, v0, v1
	s_and_saveexec_b64 s[8:9], vcc
	s_cbranch_execz .LBB0_1535
	s_add_u32 s12, s24, 0xed22200
	s_addc_u32 s13, s25, 0
	s_mov_b32 s19, 1
	s_mov_b64 s[16:17], 0
	v_mov_b32_e32 v0, 0
	s_branch .LBB0_1526

.LBB0_1539:
	s_or_b64 exec, exec, s[8:9]
	s_waitcnt vmcnt(0)
	v_readfirstlane_b32 s6, v2
	s_add_u32 s8, s24, 0xed25400
	s_addc_u32 s9, s25, 0
	s_mov_b64 s[12:13], 0
	v_add_u32_e32 v1, s6, v1
	v_add_u32_e32 v4, 1, v1
	v_mul_u32_u24_e32 v0, 11, v0
	v_cmp_ne_u32_e32 vcc, v4, v0
	v_readfirstlane_b32 s100, v0
	v_mov_b64_e32 v[0:1], s[8:9]
	s_and_saveexec_b64 s[6:7], vcc
	s_cbranch_execz .LBB0_1551
	v_mov_b32_e32 v0, 0
	global_load_dword v1, v0, s[8:9] sc1
	s_mov_b64 s[16:17], 0
	s_waitcnt vmcnt(0)
	v_cmp_gt_u32_e32 vcc, s100, v1
	s_and_saveexec_b64 s[14:15], vcc
	s_cbranch_execz .LBB0_1550
	s_add_u32 s12, s24, 0xed22200
	s_addc_u32 s13, s25, 0
	s_mov_b32 s19, 1
	s_branch .LBB0_1543
